# speedup vs baseline: 1.0099x; 1.0099x over previous
; #define SBAR() __builtin_amdgcn_sched_barrier(0)
; #define VMW() asm volatile("s_waitcnt vmcnt(0)" ::: "memory")
; __device__ __forceinline__ void partialSM(f32x16& p0, f32x16& p1, float& m_reg, float& mn, float& alpha) {
;     float pmax = p0[0];
; #pragma unroll
;     for (int r = 1; r < 16; ++r) pmax = fmaxf(pmax, p0[r]);
; #pragma unroll
;     for (int r = 0; r < 16; ++r) pmax = fmaxf(pmax, p1[r]);
;     { auto rr = __builtin_amdgcn_permlane32_swap(__float_as_uint(pmax), __float_as_uint(pmax), false, false);
;       pmax = fmaxf(__uint_as_float(rr[0]), __uint_as_float(rr[1])); }
;     constexpr float C2 = 1.4426950408889634f * ASCALE;
;     if (__builtin_expect(__all((pmax - m_reg) * ASCALE <= ATHR), 1)) { mn = m_reg; alpha = 1.f; }
;     else { mn = fmaxf(m_reg, pmax); alpha = __builtin_amdgcn_exp2f((m_reg - mn) * C2); m_reg = mn; }
;     const float mnL = -mn * C2;
; #pragma unroll
;     for (int r = 0; r < 16; ++r) p0[r] = fmaf(p0[r], C2, mnL);
; #pragma unroll
;     for (int r = 0; r < 16; ++r) p1[r] = fmaf(p1[r], C2, mnL);
; #pragma unroll
;     for (int r = 0; r < 16; ++r) p0[r] = __builtin_amdgcn_exp2f(p0[r]);
; }
; __device__ __forceinline__ void attn_block(const ABlk& cur, char* lds, ASeam& Sm, const int tid, const int wv) {
;     const int wid = __builtin_amdgcn_readfirstlane(tid >> 6), lane = tid & 63, r32 = lane & 31, hi = lane >> 5;
;     const int NT = cur.P0 / KVBLK + 4;
;     const int qlo = cur.P0 + wid * QBLK, qm = qlo + r32 - 4 * hi;
;     float* wsl = (float*)(lds + AO_W) + wid * 64; float* li_l = wsl; float* al_l = wsl + 32;
;     float m_reg = -1e30f, l_reg = 0; f32x16 o[4] = {};
;     const int sr = tid >> 4, sc = (tid & 15) * 8, vst0 = v_st(sr, sc), vst1 = v_st(32 + sr, sc), kws = KSWZ(sr, sc * 2);
;     const int rr = tid >> 3, rc = (tid & 7) * 8, rws = RSWZ(rr, rc * 2);
;     const unsigned kvo = (unsigned)(sr * 128 + sc) * 2u, rvo = (unsigned)(rr * 64 + rc) * 2u;
;     const int vb0 = (int)(uintptr_t)lds + v_rd_base(lane);
;     const u16* Kh = cur.Kn; const u16* Vh = cur.V; const u16* Rh = cur.Kr;
;     ...
;     f32x16 pA0, pA1, pB0, pB1; float mnA, mnB, alA, alB; bf16x8 pa0, pa1, pa2, pa3;
;     SWRITE_HV(0); SBAR();
;     SLOAD_H(Kh, Vh, Rh, KBASE(1));
;     SBAR(); qkt<0>(pA0, pA1, lds, r32, hi, Sm.qr);
;     MASKT(pA0, pA1, 0); partialSM(pA0, pA1, m_reg, mnA, alA);
;     VMW(); SWRITE_H(1);
;     __syncthreads();
.LBB0_407:
	s_xor_b64 s[4:5], s[66:67], -1
	v_writelane_b32 v255, s4, 19
	v_and_b32_e32 v55, 63, v55
	s_lshl_b32 s83, s72, 2
	v_writelane_b32 v255, s5, 20
	s_and_b32 s4, s70, 0x3fffffc0
	s_lshl_b32 s4, s4, 2
	s_add_i32 s71, s4, 0
	v_add_u32_e32 v206, v59, v56
	v_lshlrev_b32_e32 v56, 4, v55
	s_add_i32 s83, s83, 4
	s_add_i32 s71, s71, 0x15000
	v_lshlrev_b32_e32 v0, 3, v55
	v_and_b32_e32 v56, 0xc0, v56
	v_lshlrev_b32_e32 v59, 1, v55
	v_and_or_b32 v56, v0, 24, v56
	v_and_b32_e32 v59, 32, v59
	v_and_b32_e32 v0, 0x100, v0
	s_cmp_lg_u32 0, -1
	v_or3_b32 v0, v56, v59, v0
	s_cselect_b32 s4, 0, 0
	v_add_u32_e32 v194, s4, v0
	v_max_f32_e32 v0, v3, v3
	v_max_f32_e32 v56, v2, v2
	v_max_f32_e32 v0, v56, v0
	v_max3_f32 v0, v0, v4, v5
	v_max3_f32 v0, v0, v6, v7
	v_max3_f32 v0, v0, v8, v9
	v_max3_f32 v0, v0, v10, v11
	v_max3_f32 v0, v0, v12, v13
	v_max3_f32 v0, v0, v14, v15
	v_max3_f32 v0, v0, v16, v17
	v_max3_f32 v0, v0, v18, v19
	v_max3_f32 v0, v0, v20, v21
	v_max3_f32 v0, v0, v22, v23
	v_max3_f32 v0, v0, v24, v25
	v_max3_f32 v0, v0, v26, v27
	v_max3_f32 v0, v0, v28, v29
	v_max3_f32 v0, v0, v30, v31
	v_max3_f32 v0, v0, v32, v33
	v_mov_b32_e32 v56, v0
	s_nop 1
	v_permlane32_swap_b32_e32 v0, v56
	v_max_f32_e32 v56, v56, v56
	v_max_f32_e32 v0, v0, v0
	v_max_f32_e32 v0, v0, v56
	v_add_f32_e32 v56, 0x7149f2ca, v0
	v_mul_f32_e32 v56, 0x3d93cd3a, v56
	s_mov_b32 s4, 0x41000000
	v_cmp_ge_f32_e32 vcc, s4, v56
	s_add_i32 s4, 0, 0x12c00
	s_waitcnt vmcnt(0)
	s_waitcnt vmcnt(4)
	ds_write_b128 v202, v[34:37] offset:16384
	s_waitcnt vmcnt(3)
	ds_write_b128 v203, v[38:41] offset:16384
	v_add_u32_e32 v207, v58, v61
	v_add_u32_e32 v34, s4, v206
	s_cmp_eq_u64 vcc, exec
	s_waitcnt vmcnt(2)
	ds_write_b128 v207, v[42:45] offset:50176
	s_waitcnt vmcnt(1)
	ds_write_b128 v207, v[46:49] offset:58880
	s_waitcnt vmcnt(0)
	ds_write_b128 v34, v[50:53]
	v_max_f32_e32 v34, 0xf149f2ca, v0
	s_cselect_b64 vcc, -1, 0
	v_mov_b32_e32 v0, 0xf149f2ca
	v_cndmask_b32_e32 v210, v34, v0, vcc
	v_mul_f32_e32 v0, 0xbdd53b94, v210
	v_fmamk_f32 v2, v2, 0x3dd53b94, v0
	v_mov_b32_e32 v166, v2
	v_fmamk_f32 v2, v3, 0x3dd53b94, v0
	v_mov_b32_e32 v175, v2
	v_fmamk_f32 v2, v4, 0x3dd53b94, v0
	v_mov_b32_e32 v167, v2
	v_fmamk_f32 v2, v5, 0x3dd53b94, v0
	v_mov_b32_e32 v176, v2
	v_fmamk_f32 v2, v6, 0x3dd53b94, v0
	v_mov_b32_e32 v168, v2
	v_fmamk_f32 v2, v7, 0x3dd53b94, v0
	v_mov_b32_e32 v177, v2
	v_fmamk_f32 v2, v8, 0x3dd53b94, v0
	v_mov_b32_e32 v169, v2
	v_fmamk_f32 v2, v9, 0x3dd53b94, v0
	v_mov_b32_e32 v174, v2
	v_fmamk_f32 v2, v10, 0x3dd53b94, v0
	v_mov_b32_e32 v165, v2
	v_fmamk_f32 v2, v11, 0x3dd53b94, v0
	v_pk_fma_f32 v[150:151], v[24:25], s[84:85], v[0:1] op_sel_hi:[1,0,0]
	v_sub_f32_e32 v24, 0xf149f2ca, v34
	v_mov_b32_e32 v170, v2
	v_fmamk_f32 v2, v12, 0x3dd53b94, v0
	v_mul_f32_e32 v24, 0x3dd53b94, v24
	v_mov_b32_e32 v171, v2
	v_fmamk_f32 v2, v13, 0x3dd53b94, v0
	v_exp_f32_e32 v24, v24
	v_mov_b32_e32 v172, v2
	v_fmamk_f32 v2, v14, 0x3dd53b94, v0
	v_mov_b32_e32 v162, v2
	v_fmamk_f32 v2, v15, 0x3dd53b94, v0
	v_mul_u32_u24_e32 v62, 0x90, v54
	v_pk_fma_f32 v[148:149], v[32:33], s[84:85], v[0:1] op_sel_hi:[1,0,0]
	v_pk_fma_f32 v[152:153], v[30:31], s[84:85], v[0:1] op_sel_hi:[1,0,0]
	v_pk_fma_f32 v[156:157], v[28:29], s[84:85], v[0:1] op_sel_hi:[1,0,0]
	v_pk_fma_f32 v[146:147], v[26:27], s[84:85], v[0:1] op_sel_hi:[1,0,0]
	v_pk_fma_f32 v[154:155], v[22:23], s[84:85], v[0:1] op_sel_hi:[1,0,0]
	v_pk_fma_f32 v[158:159], v[20:21], s[84:85], v[0:1] op_sel_hi:[1,0,0]
	v_pk_fma_f32 v[160:161], v[18:19], s[84:85], v[0:1] op_sel_hi:[1,0,0]
	v_mov_b32_e32 v164, v2
	v_fmamk_f32 v2, v16, 0x3dd53b94, v0
	v_fmac_f32_e32 v0, 0x3dd53b94, v17
	s_add_i32 s6, s33, 0xffffff80
	v_mov_b32_e32 v163, v2
	v_mov_b32_e32 v173, v0
	v_add_u32_e32 v16, s4, v62
	v_add_u32_e32 v0, s6, v54
	v_mov_b32_e32 v14, v1
	v_mov_b32_e32 v15, v1
	v_cndmask_b32_e64 v208, v24, 1.0, vcc
	v_cmp_gt_u32_e64 s[4:5], 32, v55
	v_lshl_add_u32 v195, v54, 2, s71
	v_lshl_add_u32 v198, v57, 2, s71
	v_sub_u32_e32 v209, v0, v57
	v_mov_b32_e32 v0, v1
	v_mov_b32_e32 v2, v1
	v_mov_b32_e32 v3, v1
	v_mov_b32_e32 v4, v1
	v_mov_b32_e32 v5, v1
	v_mov_b32_e32 v6, v1
	v_mov_b32_e32 v7, v1
	v_mov_b32_e32 v8, v1
	v_mov_b32_e32 v9, v1
	v_mov_b32_e32 v10, v1
	v_mov_b32_e32 v11, v1
	v_mov_b32_e32 v12, v1
	v_mov_b32_e32 v13, v1
	v_add_u32_e32 v205, v16, v60
	v_mov_b64_e32 v[64:65], v[14:15]
	v_mov_b64_e32 v[48:49], v[14:15]
	v_mov_b64_e32 v[32:33], v[14:15]
	v_readlane_b32 s76, v255, 13
	v_mov_b64_e32 v[62:63], v[12:13]
	v_mov_b64_e32 v[60:61], v[10:11]
	v_mov_b64_e32 v[58:59], v[8:9]
	v_mov_b64_e32 v[56:57], v[6:7]
	v_mov_b64_e32 v[54:55], v[4:5]
	v_mov_b64_e32 v[52:53], v[2:3]
	v_mov_b64_e32 v[50:51], v[0:1]
	v_mov_b64_e32 v[46:47], v[12:13]
	v_mov_b64_e32 v[44:45], v[10:11]
	v_mov_b64_e32 v[42:43], v[8:9]
	v_mov_b64_e32 v[40:41], v[6:7]
	v_mov_b64_e32 v[38:39], v[4:5]
	v_mov_b64_e32 v[36:37], v[2:3]
	v_mov_b64_e32 v[34:35], v[0:1]
	v_mov_b64_e32 v[30:31], v[12:13]
	v_mov_b64_e32 v[28:29], v[10:11]
	v_mov_b64_e32 v[26:27], v[8:9]
	v_mov_b64_e32 v[24:25], v[6:7]
	v_mov_b64_e32 v[22:23], v[4:5]
	v_mov_b64_e32 v[20:21], v[2:3]
	v_mov_b64_e32 v[18:19], v[0:1]
	v_mov_b64_e32 v[16:17], v[14:15]
	s_mov_b32 s82, 2
	v_mov_b32_e32 v196, 0
	s_movk_i32 s70, 0xbf
	v_readlane_b32 s77, v255, 14
	v_mov_b64_e32 v[14:15], v[12:13]
	v_mov_b64_e32 v[12:13], v[10:11]
	v_mov_b64_e32 v[10:11], v[8:9]
	v_mov_b64_e32 v[8:9], v[6:7]
	v_mov_b64_e32 v[6:7], v[4:5]
	v_mov_b64_e32 v[4:5], v[2:3]
	v_mov_b64_e32 v[2:3], v[0:1]
	s_waitcnt lgkmcnt(0)
	s_barrier
; __device__ __forceinline__ void finishSM(f32x16& p0, f32x16& p1, float alpha, float& l_reg, bf16x8& pa0, bf16x8& pa1, bf16x8& pa2, bf16x8& pa3) {
; #pragma unroll
;     for (int r = 0; r < 16; ++r) p1[r] = __builtin_amdgcn_exp2f(p1[r]);
;     float ps = 0;
; #pragma unroll
;     for (int r = 0; r < 16; ++r) ps += p0[r];
; #pragma unroll
;     for (int r = 0; r < 16; ++r) ps += p1[r];
;     { auto rr = __builtin_amdgcn_permlane32_swap(__float_as_uint(ps), __float_as_uint(ps), false, false);
;       ps = __uint_as_float(rr[0]) + __uint_as_float(rr[1]); }
;     l_reg = l_reg * alpha + ps;
;     ...
;     PK4(p0, 0, pa0); PK4(p0, 8, pa1); PK4(p1, 0, pa2); PK4(p1, 8, pa3);
;     ...
; }
; template <int KB>
; __device__ __forceinline__ void qkt(f32x16& p0, f32x16& p1, const char* lds, int r32, int hi, const bf16x8* qr) {
;     p0 = f32x16{}; p1 = f32x16{};
;     const char* kb = lds + AO_K + KB * SHM_K + KSWZ(r32, hi * 16); const char* rb = lds + AO_R + KB * SHM_R + RSWZ(r32, hi * 16);
; #pragma unroll
;     for (int d0 = 0; d0 < 8; ++d0) { const char* a = kb + d0 * 32;
;         bf16x8 b0 = *reinterpret_cast<const bf16x8*>(a);
;         bf16x8 b1 = *reinterpret_cast<const bf16x8*>(a + 32 * KPITCH);
;         p0 = __builtin_amdgcn_mfma_f32_32x32x16_bf16(b0, qr[d0], p0, 0, 0, 0);
;         p1 = __builtin_amdgcn_mfma_f32_32x32x16_bf16(b1, qr[d0], p1, 0, 0, 0); }
; #pragma unroll
;     for (int d0 = 0; d0 < 4; ++d0) { const char* a = rb + d0 * 32;
;         bf16x8 b0 = *reinterpret_cast<const bf16x8*>(a);
;         bf16x8 b1 = *reinterpret_cast<const bf16x8*>(a + 32 * RPITCH);
;         p0 = __builtin_amdgcn_mfma_f32_32x32x16_bf16(b0, qr[8 + d0], p0, 0, 0, 0);
;         p1 = __builtin_amdgcn_mfma_f32_32x32x16_bf16(b1, qr[8 + d0], p1, 0, 0, 0); }
; }
.LBB0_408:
	ds_read_b128 v[70:73], v200 offset:50176
	ds_read_b128 v[66:69], v200 offset:58880
	ds_read_b128 v[178:181], v200 offset:50208
	ds_read_b128 v[212:215], v200 offset:58912
	ds_read_b128 v[242:245], v200 offset:50240
	ds_read_b128 v[246:249], v200 offset:58944
	v_exp_f32_e32 v166, v166
	v_exp_f32_e32 v175, v175
	v_exp_f32_e32 v167, v167
	v_exp_f32_e32 v176, v176
	s_waitcnt lgkmcnt(4)
	v_mfma_f32_32x32x16_bf16 v[82:97], v[70:73], v[142:145], 0
	v_exp_f32_e32 v168, v168
	v_exp_f32_e32 v177, v177
	v_exp_f32_e32 v169, v169
	v_exp_f32_e32 v174, v174
	v_mfma_f32_32x32x16_bf16 v[66:81], v[66:69], v[142:145], 0
	v_exp_f32_e32 v165, v165
	v_exp_f32_e32 v170, v170
	v_exp_f32_e32 v171, v171
	s_waitcnt lgkmcnt(2)
	v_mfma_f32_32x32x16_bf16 v[66:81], v[212:215], v[138:141], v[66:81]
	v_exp_f32_e32 v172, v172
	v_exp_f32_e32 v162, v162
	v_exp_f32_e32 v164, v164
	v_exp_f32_e32 v163, v163
	v_mfma_f32_32x32x16_bf16 v[82:97], v[178:181], v[138:141], v[82:97]
	ds_read_b128 v[178:181], v200 offset:50272
	ds_read_b128 v[212:215], v200 offset:58976
	v_exp_f32_e32 v173, v173
	v_exp_f32_e32 v0, v160
	v_exp_f32_e32 v160, v161
	s_waitcnt lgkmcnt(2)
	v_mfma_f32_32x32x16_bf16 v[66:81], v[246:249], v[134:137], v[66:81]
	v_add_f32_e32 v161, 0, v166
	v_add_f32_e32 v161, v175, v161
	v_add_f32_e32 v161, v167, v161
	v_add_f32_e32 v161, v176, v161
	v_mfma_f32_32x32x16_bf16 v[82:97], v[242:245], v[134:137], v[82:97]
	ds_read_b128 v[242:245], v200 offset:50304
	ds_read_b128 v[246:249], v200 offset:59008
	v_add_f32_e32 v161, v168, v161
	v_add_f32_e32 v161, v177, v161
	v_add_f32_e32 v161, v169, v161
	s_waitcnt lgkmcnt(2)
	v_mfma_f32_32x32x16_bf16 v[66:81], v[212:215], v[130:133], v[66:81]
	v_add_f32_e32 v161, v174, v161
	v_add_f32_e32 v161, v165, v161
	v_add_f32_e32 v161, v170, v161
	v_add_f32_e32 v161, v171, v161
	v_mfma_f32_32x32x16_bf16 v[82:97], v[178:181], v[130:133], v[82:97]
	ds_read_b128 v[178:181], v200 offset:50336
	ds_read_b128 v[212:215], v200 offset:59040
	v_add_f32_e32 v161, v172, v161
	v_add_f32_e32 v161, v162, v161
	v_add_f32_e32 v161, v164, v161
	v_exp_f32_e32 v158, v158
	s_waitcnt lgkmcnt(2)
	v_mfma_f32_32x32x16_bf16 v[66:81], v[246:249], v[126:129], v[66:81]
	v_add_f32_e32 v161, v163, v161
	v_exp_f32_e32 v159, v159
	v_add_f32_e32 v161, v173, v161
	v_mfma_f32_32x32x16_bf16 v[82:97], v[242:245], v[126:129], v[82:97]
	ds_read_b128 v[242:245], v200 offset:50368
	ds_read_b128 v[246:249], v200 offset:59072
	v_exp_f32_e32 v154, v154
	v_add_f32_e32 v161, v0, v161
	v_exp_f32_e32 v155, v155
	v_add_f32_e32 v161, v160, v161
	s_waitcnt lgkmcnt(2)
	v_mfma_f32_32x32x16_bf16 v[66:81], v[212:215], v[122:125], v[66:81]
	v_exp_f32_e32 v150, v150
	v_add_f32_e32 v161, v158, v161
	v_exp_f32_e32 v151, v151
	v_mfma_f32_32x32x16_bf16 v[82:97], v[178:181], v[122:125], v[82:97]
	ds_read_b128 v[178:181], v200 offset:50400
	ds_read_b128 v[212:215], v200 offset:59104
	v_add_f32_e32 v161, v159, v161
	v_exp_f32_e32 v146, v146
	v_add_f32_e32 v161, v154, v161
	v_exp_f32_e32 v147, v147
	s_waitcnt lgkmcnt(2)
	v_mfma_f32_32x32x16_bf16 v[66:81], v[246:249], v[118:121], v[66:81]
	v_add_f32_e32 v161, v155, v161
	v_exp_f32_e32 v156, v156
	v_add_f32_e32 v161, v150, v161
	v_mfma_f32_32x32x16_bf16 v[82:97], v[242:245], v[118:121], v[82:97]
	ds_read_b128 v[242:245], v205
	ds_read_b128 v[246:249], v205 offset:4608
	v_exp_f32_e32 v157, v157
	v_add_f32_e32 v161, v151, v161
	v_exp_f32_e32 v152, v152
	v_add_f32_e32 v161, v146, v161
	s_waitcnt lgkmcnt(2)
	v_mfma_f32_32x32x16_bf16 v[66:81], v[212:215], v[110:113], v[66:81]
	v_exp_f32_e32 v153, v153
	v_add_f32_e32 v161, v147, v161
	v_exp_f32_e32 v148, v148
	v_add_f32_e32 v161, v156, v161
	v_mfma_f32_32x32x16_bf16 v[82:97], v[178:181], v[110:113], v[82:97]
	ds_read_b128 v[178:181], v205 offset:32
	ds_read_b128 v[212:215], v205 offset:4640
	v_exp_f32_e32 v149, v149
	v_add_f32_e32 v161, v157, v161
	v_add_f32_e32 v161, v152, v161
	s_waitcnt lgkmcnt(2)
	v_mfma_f32_32x32x16_bf16 v[66:81], v[246:249], v[114:117], v[66:81]
	v_add_f32_e32 v161, v153, v161
	v_add_f32_e32 v161, v148, v161
	v_add_f32_e32 v211, v149, v161
	v_cvt_pk_bf16_f32 v166, v166, v175
	v_mfma_f32_32x32x16_bf16 v[82:97], v[242:245], v[114:117], v[82:97]
	ds_read_b128 v[242:245], v205 offset:64
	ds_read_b128 v[246:249], v205 offset:4672
	v_cvt_pk_bf16_f32 v167, v167, v176
	v_cvt_pk_bf16_f32 v168, v168, v177
	v_cvt_pk_bf16_f32 v169, v169, v174
	s_waitcnt lgkmcnt(2)
	v_mfma_f32_32x32x16_bf16 v[82:97], v[178:181], v[106:109], v[82:97]
	v_cvt_pk_bf16_f32 v170, v165, v170
	v_cvt_pk_bf16_f32 v171, v171, v172
	v_cvt_pk_bf16_f32 v172, v162, v164
	v_cvt_pk_bf16_f32 v173, v163, v173
	v_mfma_f32_32x32x16_bf16 v[66:81], v[212:215], v[106:109], v[66:81]
	ds_read_b128 v[178:181], v205 offset:96
	ds_read_b128 v[212:215], v205 offset:4704
	v_cvt_pk_bf16_f32 v174, v0, v160
	v_cvt_pk_bf16_f32 v175, v158, v159
	v_cvt_pk_bf16_f32 v176, v154, v155
	s_waitcnt lgkmcnt(2)
	v_mfma_f32_32x32x16_bf16 v[82:97], v[242:245], v[102:105], v[82:97]
	v_cvt_pk_bf16_f32 v177, v150, v151
	v_permlane32_swap_b32_e32 v166, v168
	v_permlane32_swap_b32_e32 v167, v169
	v_permlane32_swap_b32_e32 v170, v172
	v_mfma_f32_32x32x16_bf16 v[66:81], v[246:249], v[102:105], v[66:81]
	v_permlane32_swap_b32_e32 v171, v173
	v_permlane32_swap_b32_e32 v174, v176
	v_permlane32_swap_b32_e32 v175, v177
	s_waitcnt lgkmcnt(0)
; __device__ __forceinline__ void mask_tile(f32x16& p0, f32x16& p1, int dq) {
;     const float NEG = -__builtin_inff();
; #pragma unroll
;     for (int r = 0; r < 16; ++r) { const int c = (r & 3) + 8 * (r >> 2);
;         if (dq - c < 0) p0[r] = NEG;
;         if (dq - c - 32 < 0) p1[r] = NEG; }
; }
	v_mfma_f32_32x32x16_bf16 v[82:97], v[178:181], v[98:101], v[82:97]
	v_cvt_pk_bf16_f32 v178, v146, v147
	v_cvt_pk_bf16_f32 v179, v156, v157
	v_cvt_pk_bf16_f32 v180, v152, v153
	v_cvt_pk_bf16_f32 v181, v148, v149
	s_nop 0
	v_permlane32_swap_b32_e32 v178, v180
	v_mfma_f32_32x32x16_bf16 v[66:81], v[212:215], v[98:101], v[66:81]
	v_mov_b32_e32 v212, v211
	s_nop 1
	v_permlane32_swap_b32_e32 v211, v212
	v_permlane32_swap_b32_e32 v179, v181
	ds_read_b64_tr_b16 v[214:215], v194 offset:0
	ds_read_b64_tr_b16 v[216:217], v194 offset:0x800
	ds_read_b64_tr_b16 v[218:219], v194 offset:0x1000
	ds_read_b64_tr_b16 v[220:221], v194 offset:0x1800
	ds_read_b64_tr_b16 v[222:223], v194 offset:0x2000
	ds_read_b64_tr_b16 v[224:225], v194 offset:0x2800
	ds_read_b64_tr_b16 v[226:227], v194 offset:0x3000
	ds_read_b64_tr_b16 v[228:229], v194 offset:0x3800
	s_add_u32 s74, s76, s96
	v_mov_b32_e32 v0, v201
	v_mov_b32_e32 v162, v199
	s_addc_u32 s75, s77, s97
	s_mov_b32 s6, 0x1d988000
	v_lshl_add_u64 v[154:155], s[74:75], 0, v[0:1]
	v_add_co_u32_e32 v146, vcc, s6, v154
	s_mov_b32 s6, 0x1d98a000
	s_nop 0
	v_addc_co_u32_e32 v147, vcc, 0, v155, vcc
	v_add_co_u32_e32 v150, vcc, s6, v154
	s_mov_b32 s6, 0x1b988000
	s_nop 0
	v_addc_co_u32_e32 v151, vcc, 0, v155, vcc
	v_add_co_u32_e32 v156, vcc, s6, v154
	s_mov_b32 s6, 0x1b98a000
	s_nop 0
	v_addc_co_u32_e32 v157, vcc, 0, v155, vcc
	s_add_u32 s80, s88, s96
	v_add_co_u32_e32 v158, vcc, s6, v154
	v_mov_b32_e32 v163, v1
	s_addc_u32 s81, s89, s97
	v_addc_co_u32_e32 v159, vcc, 0, v155, vcc
	v_lshl_add_u64 v[162:163], s[80:81], 0, v[162:163]
	s_mov_b32 s6, 0x18884000
	v_add_co_u32_e32 v162, vcc, s6, v162
	global_load_dwordx4 v[146:149], v[146:147], off
	s_nop 0
	global_load_dwordx4 v[150:153], v[150:151], off
	v_addc_co_u32_e32 v163, vcc, 0, v163, vcc
	global_load_dwordx4 v[154:157], v[156:157], off
	s_nop 0
	global_load_dwordx4 v[158:161], v[158:159], off
	s_nop 0
	global_load_dwordx4 v[162:165], v[162:163], off
	s_sub_i32 s6, s70, 64
	s_cmp_le_i32 s6, s33
	s_cbranch_scc1 .LBB0_410
	v_add_u32_e32 v0, 64, v209
	v_cmp_gt_i32_e64 s[64:65], 26, v0
	v_cmp_gt_i32_e64 s[66:67], 27, v0
	v_cmp_gt_i32_e64 s[62:63], 25, v0
	s_and_b64 s[64:65], s[66:67], s[64:65]
	v_cmp_gt_i32_e64 s[60:61], 24, v0
	s_and_b64 s[62:63], s[64:65], s[62:63]
	v_cmp_gt_i32_e64 s[58:59], 19, v0
	s_and_b64 s[60:61], s[62:63], s[60:61]
	v_cmp_gt_i32_e64 s[56:57], 18, v0
	s_and_b64 s[58:59], s[60:61], s[58:59]
	v_cmp_gt_i32_e64 s[54:55], 17, v0
	s_and_b64 s[56:57], s[58:59], s[56:57]
	v_cmp_gt_i32_e64 s[52:53], 16, v0
	s_and_b64 s[54:55], s[56:57], s[54:55]
	v_cmp_gt_i32_e64 s[50:51], 11, v0
	s_and_b64 s[52:53], s[54:55], s[52:53]
	v_cmp_gt_i32_e64 s[48:49], 10, v0
	s_and_b64 s[50:51], s[52:53], s[50:51]
	v_cmp_gt_i32_e64 s[46:47], 9, v0
	s_and_b64 s[48:49], s[50:51], s[48:49]
	v_cmp_gt_i32_e64 s[44:45], 8, v0
	s_and_b64 s[46:47], s[48:49], s[46:47]
	v_cmp_gt_i32_e64 s[42:43], 3, v0
	s_and_b64 s[44:45], s[46:47], s[44:45]
	v_cmp_gt_i32_e64 s[40:41], 2, v0
	s_and_b64 s[42:43], s[44:45], s[42:43]
	v_cmp_gt_i32_e64 s[38:39], 1, v0
	s_and_b64 s[40:41], s[42:43], s[40:41]
	v_cmp_gt_i32_e64 s[36:37], 0, v0
	s_and_b64 s[38:39], s[40:41], s[38:39]
	s_and_b64 s[36:37], s[38:39], s[36:37]
	v_cmp_gt_i32_e64 s[34:35], 58, v0
	v_cndmask_b32_e64 v82, v82, v186, s[36:37]
	v_cmp_gt_i32_e64 s[36:37], 59, v0
	v_cmp_gt_i32_e64 s[30:31], 57, v0
	s_and_b64 s[34:35], s[36:37], s[34:35]
	v_cmp_gt_i32_e64 s[28:29], 56, v0
	s_and_b64 s[30:31], s[34:35], s[30:31]
	v_cmp_gt_i32_e64 s[26:27], 51, v0
	s_and_b64 s[28:29], s[30:31], s[28:29]
	v_cmp_gt_i32_e64 s[24:25], 50, v0
	s_and_b64 s[26:27], s[28:29], s[26:27]
	v_cmp_gt_i32_e64 s[22:23], 49, v0
	s_and_b64 s[24:25], s[26:27], s[24:25]
	v_cmp_gt_i32_e64 s[20:21], 48, v0
	s_and_b64 s[22:23], s[24:25], s[22:23]
	v_cmp_gt_i32_e64 s[18:19], 43, v0
	s_and_b64 s[20:21], s[22:23], s[20:21]
	v_cmp_gt_i32_e64 s[16:17], 42, v0
	s_and_b64 s[18:19], s[20:21], s[18:19]
	v_cmp_gt_i32_e64 s[14:15], 41, v0
	s_and_b64 s[16:17], s[18:19], s[16:17]
	v_cmp_gt_i32_e64 s[12:13], 40, v0
	s_and_b64 s[14:15], s[16:17], s[14:15]
	v_cmp_gt_i32_e64 s[10:11], 35, v0
	s_and_b64 s[12:13], s[14:15], s[12:13]
	v_cmp_gt_i32_e64 s[8:9], 34, v0
	s_and_b64 s[10:11], s[12:13], s[10:11]
	v_cmp_gt_i32_e64 s[6:7], 33, v0
	s_and_b64 s[8:9], s[10:11], s[8:9]
	v_cmp_gt_i32_e32 vcc, 32, v0
	s_and_b64 s[6:7], s[8:9], s[6:7]
	s_and_b64 vcc, s[6:7], vcc
	v_cndmask_b32_e64 v97, v97, v186, s[66:67]
	v_cndmask_b32_e64 v96, v96, v186, s[64:65]
	v_cndmask_b32_e64 v95, v95, v186, s[62:63]
	v_cndmask_b32_e64 v94, v94, v186, s[60:61]
	v_cndmask_b32_e64 v93, v93, v186, s[58:59]
	v_cndmask_b32_e64 v92, v92, v186, s[56:57]
	v_cndmask_b32_e64 v91, v91, v186, s[54:55]
	v_cndmask_b32_e64 v90, v90, v186, s[52:53]
	v_cndmask_b32_e64 v89, v89, v186, s[50:51]
	v_cndmask_b32_e64 v88, v88, v186, s[48:49]
	v_cndmask_b32_e64 v87, v87, v186, s[46:47]
	v_cndmask_b32_e64 v86, v86, v186, s[44:45]
	v_cndmask_b32_e64 v85, v85, v186, s[42:43]
	v_cndmask_b32_e64 v84, v84, v186, s[40:41]
	v_cndmask_b32_e64 v83, v83, v186, s[38:39]
	v_cndmask_b32_e64 v81, v81, v186, s[36:37]
	v_cndmask_b32_e64 v80, v80, v186, s[34:35]
	v_cndmask_b32_e64 v79, v79, v186, s[30:31]
	v_cndmask_b32_e64 v78, v78, v186, s[28:29]
	v_cndmask_b32_e64 v77, v77, v186, s[26:27]
	v_cndmask_b32_e64 v76, v76, v186, s[24:25]
	v_cndmask_b32_e64 v75, v75, v186, s[22:23]
	v_cndmask_b32_e64 v74, v74, v186, s[20:21]
	v_cndmask_b32_e64 v73, v73, v186, s[18:19]
	v_cndmask_b32_e64 v72, v72, v186, s[16:17]
	v_cndmask_b32_e64 v71, v71, v186, s[14:15]
	v_cndmask_b32_e64 v70, v70, v186, s[12:13]
	v_cndmask_b32_e64 v69, v69, v186, s[10:11]
	v_cndmask_b32_e64 v68, v68, v186, s[8:9]
	v_cndmask_b32_e64 v67, v67, v186, s[6:7]
	v_cndmask_b32_e32 v66, v66, v186, vcc

; __device__ __forceinline__ void partialSM(f32x16& p0, f32x16& p1, float& m_reg, float& mn, float& alpha) {
;     ...
;     constexpr float C2 = 1.4426950408889634f * ASCALE;
;     if (__builtin_expect(__all((pmax - m_reg) * ASCALE <= ATHR), 1)) { mn = m_reg; alpha = 1.f; }
;     else { mn = fmaxf(m_reg, pmax); alpha = __builtin_amdgcn_exp2f((m_reg - mn) * C2); m_reg = mn; }
;     const float mnL = -mn * C2;
; #pragma unroll
;     for (int r = 0; r < 16; ++r) p0[r] = fmaf(p0[r], C2, mnL);
; #pragma unroll
;     for (int r = 0; r < 16; ++r) p1[r] = fmaf(p1[r], C2, mnL);
; #pragma unroll
;     for (int r = 0; r < 16; ++r) p0[r] = __builtin_amdgcn_exp2f(p0[r]);
; }
; __device__ __forceinline__ void finishSM(f32x16& p0, f32x16& p1, float alpha, float& l_reg, bf16x8& pa0, bf16x8& pa1, bf16x8& pa2, bf16x8& pa3) {
; #pragma unroll
;     for (int r = 0; r < 16; ++r) p1[r] = __builtin_amdgcn_exp2f(p1[r]);
;     float ps = 0;
; #pragma unroll
;     for (int r = 0; r < 16; ++r) ps += p0[r];
; #pragma unroll
;     for (int r = 0; r < 16; ++r) ps += p1[r];
;     { auto rr = __builtin_amdgcn_permlane32_swap(__float_as_uint(ps), __float_as_uint(ps), false, false);
;       ps = __uint_as_float(rr[0]) + __uint_as_float(rr[1]); }
;     l_reg = l_reg * alpha + ps;
; template <int KB>
; __device__ __forceinline__ void qkt(f32x16& p0, f32x16& p1, const char* lds, int r32, int hi, const bf16x8* qr) {
;     p0 = f32x16{}; p1 = f32x16{};
;     const char* kb = lds + AO_K + KB * SHM_K + KSWZ(r32, hi * 16); const char* rb = lds + AO_R + KB * SHM_R + RSWZ(r32, hi * 16);
; #pragma unroll
;     for (int d0 = 0; d0 < 8; ++d0) { const char* a = kb + d0 * 32;
;         bf16x8 b0 = *reinterpret_cast<const bf16x8*>(a);
;         bf16x8 b1 = *reinterpret_cast<const bf16x8*>(a + 32 * KPITCH);
;         p0 = __builtin_amdgcn_mfma_f32_32x32x16_bf16(b0, qr[d0], p0, 0, 0, 0);
;         p1 = __builtin_amdgcn_mfma_f32_32x32x16_bf16(b1, qr[d0], p1, 0, 0, 0); }
; #pragma unroll
;     for (int d0 = 0; d0 < 4; ++d0) { const char* a = rb + d0 * 32;
;         bf16x8 b0 = *reinterpret_cast<const bf16x8*>(a);
;         bf16x8 b1 = *reinterpret_cast<const bf16x8*>(a + 32 * RPITCH);
;         p0 = __builtin_amdgcn_mfma_f32_32x32x16_bf16(b0, qr[8 + d0], p0, 0, 0, 0);
;         p1 = __builtin_amdgcn_mfma_f32_32x32x16_bf16(b1, qr[8 + d0], p1, 0, 0, 0); }
; }
.LBB0_414:
	v_cndmask_b32_e64 v210, v0, v210, s[6:7]
	v_mul_f32_e32 v181, 0xbdd53b94, v210
	v_fmamk_f32 v166, v82, 0x3dd53b94, v181
	v_fmamk_f32 v180, v83, 0x3dd53b94, v181
	v_fmamk_f32 v167, v84, 0x3dd53b94, v181
	v_fmamk_f32 v179, v85, 0x3dd53b94, v181
	v_fmamk_f32 v168, v86, 0x3dd53b94, v181
	v_fmamk_f32 v178, v87, 0x3dd53b94, v181
	v_fmamk_f32 v169, v88, 0x3dd53b94, v181
	v_fmamk_f32 v177, v89, 0x3dd53b94, v181
	v_fmamk_f32 v170, v90, 0x3dd53b94, v181
	v_fmamk_f32 v176, v91, 0x3dd53b94, v181
	v_fmamk_f32 v171, v92, 0x3dd53b94, v181
	v_fmamk_f32 v175, v93, 0x3dd53b94, v181
	v_fmamk_f32 v172, v94, 0x3dd53b94, v181
	v_fmamk_f32 v174, v95, 0x3dd53b94, v181
	v_fmamk_f32 v0, v96, 0x3dd53b94, v181
	v_fmamk_f32 v173, v97, 0x3dd53b94, v181
	v_fmamk_f32 v223, v66, 0x3dd53b94, v181
	v_fmamk_f32 v224, v67, 0x3dd53b94, v181
	v_fmamk_f32 v225, v68, 0x3dd53b94, v181
	v_fmamk_f32 v226, v69, 0x3dd53b94, v181
	v_fmamk_f32 v227, v70, 0x3dd53b94, v181
	v_fmamk_f32 v216, v71, 0x3dd53b94, v181
	v_fmamk_f32 v217, v72, 0x3dd53b94, v181
	v_fmamk_f32 v218, v73, 0x3dd53b94, v181
	v_fmamk_f32 v219, v74, 0x3dd53b94, v181
	v_fmamk_f32 v220, v75, 0x3dd53b94, v181
	v_fmamk_f32 v221, v76, 0x3dd53b94, v181
	v_fmamk_f32 v222, v77, 0x3dd53b94, v181
	v_fmamk_f32 v215, v78, 0x3dd53b94, v181
	v_fmamk_f32 v228, v79, 0x3dd53b94, v181
	v_fmamk_f32 v229, v80, 0x3dd53b94, v181
	v_fmac_f32_e32 v181, 0x3dd53b94, v81
	s_waitcnt lgkmcnt(0)
	s_barrier
	ds_read_b128 v[70:73], v200 offset:32768
	ds_read_b128 v[66:69], v200 offset:41472
	ds_read_b128 v[230:233], v200 offset:32800
	ds_read_b128 v[234:237], v200 offset:41504
	ds_read_b128 v[242:245], v200 offset:32832
	ds_read_b128 v[246:249], v200 offset:41536
	v_exp_f32_e32 v166, v166
	v_exp_f32_e32 v180, v180
	v_exp_f32_e32 v167, v167
	v_exp_f32_e32 v179, v179
	s_waitcnt lgkmcnt(4)
	v_mfma_f32_32x32x16_bf16 v[82:97], v[70:73], v[142:145], 0
	v_exp_f32_e32 v168, v168
	v_exp_f32_e32 v178, v178
	v_exp_f32_e32 v169, v169
	v_exp_f32_e32 v177, v177
	v_mfma_f32_32x32x16_bf16 v[66:81], v[66:69], v[142:145], 0
	v_exp_f32_e32 v170, v170
	v_exp_f32_e32 v176, v176
	v_exp_f32_e32 v171, v171
	v_exp_f32_e32 v175, v175
	s_waitcnt lgkmcnt(2)
	v_mfma_f32_32x32x16_bf16 v[66:81], v[234:237], v[138:141], v[66:81]
	v_exp_f32_e32 v172, v172
	v_exp_f32_e32 v174, v174
	v_exp_f32_e32 v173, v173
	v_exp_f32_e32 v0, v0
	v_mfma_f32_32x32x16_bf16 v[82:97], v[230:233], v[138:141], v[82:97]
	ds_read_b128 v[230:233], v200 offset:32864
	ds_read_b128 v[234:237], v200 offset:41568
	v_exp_f32_e32 v192, v225
	v_exp_f32_e32 v225, v215
	v_add_f32_e32 v215, 0, v166
	v_add_f32_e32 v215, v180, v215
	s_waitcnt lgkmcnt(2)
	v_mfma_f32_32x32x16_bf16 v[66:81], v[246:249], v[134:137], v[66:81]
	v_add_f32_e32 v215, v167, v215
	v_add_f32_e32 v215, v179, v215
	v_add_f32_e32 v215, v168, v215
	v_add_f32_e32 v215, v178, v215
	v_mfma_f32_32x32x16_bf16 v[82:97], v[242:245], v[134:137], v[82:97]
	ds_read_b128 v[242:245], v200 offset:32896
	ds_read_b128 v[246:249], v200 offset:41600
	v_add_f32_e32 v215, v169, v215
	v_add_f32_e32 v215, v177, v215
	v_add_f32_e32 v215, v170, v215
	v_add_f32_e32 v215, v176, v215
	s_waitcnt lgkmcnt(2)
	v_mfma_f32_32x32x16_bf16 v[66:81], v[234:237], v[130:133], v[66:81]
	v_add_f32_e32 v215, v171, v215
	v_add_f32_e32 v215, v175, v215
	v_exp_f32_e32 v190, v223
	v_add_f32_e32 v215, v172, v215
	v_mfma_f32_32x32x16_bf16 v[82:97], v[230:233], v[130:133], v[82:97]
	ds_read_b128 v[230:233], v200 offset:32928
	ds_read_b128 v[234:237], v200 offset:41632
	v_exp_f32_e32 v191, v224
	v_add_f32_e32 v215, v174, v215
	v_add_f32_e32 v215, v0, v215
	v_exp_f32_e32 v193, v226
	s_waitcnt lgkmcnt(2)
	v_mfma_f32_32x32x16_bf16 v[66:81], v[246:249], v[126:129], v[66:81]
	v_add_f32_e32 v215, v173, v215
	v_exp_f32_e32 v223, v227
	v_add_f32_e32 v215, v190, v215
	v_exp_f32_e32 v224, v216
	v_mfma_f32_32x32x16_bf16 v[82:97], v[242:245], v[126:129], v[82:97]
	ds_read_b128 v[242:245], v200 offset:32960
	ds_read_b128 v[246:249], v200 offset:41664
	v_add_f32_e32 v215, v191, v215
	v_exp_f32_e32 v217, v217
	v_add_f32_e32 v215, v192, v215
	v_exp_f32_e32 v218, v218
	s_waitcnt lgkmcnt(2)
; __device__ __forceinline__ void finishSM(f32x16& p0, f32x16& p1, float alpha, float& l_reg, bf16x8& pa0, bf16x8& pa1, bf16x8& pa2, bf16x8& pa3) {
; #pragma unroll
;     for (int r = 0; r < 16; ++r) p1[r] = __builtin_amdgcn_exp2f(p1[r]);
;     float ps = 0;
; #pragma unroll
;     for (int r = 0; r < 16; ++r) ps += p0[r];
; #pragma unroll
;     for (int r = 0; r < 16; ++r) ps += p1[r];
;     { auto rr = __builtin_amdgcn_permlane32_swap(__float_as_uint(ps), __float_as_uint(ps), false, false);
;       ps = __uint_as_float(rr[0]) + __uint_as_float(rr[1]); }
;     l_reg = l_reg * alpha + ps;
;     ...
;     PK4(p0, 0, pa0); PK4(p0, 8, pa1); PK4(p1, 0, pa2); PK4(p1, 8, pa3);
;     ...
; }
; template <int KB>
; __device__ __forceinline__ void qkt(f32x16& p0, f32x16& p1, const char* lds, int r32, int hi, const bf16x8* qr) {
;     p0 = f32x16{}; p1 = f32x16{};
;     const char* kb = lds + AO_K + KB * SHM_K + KSWZ(r32, hi * 16); const char* rb = lds + AO_R + KB * SHM_R + RSWZ(r32, hi * 16);
; #pragma unroll
;     for (int d0 = 0; d0 < 8; ++d0) { const char* a = kb + d0 * 32;
;         bf16x8 b0 = *reinterpret_cast<const bf16x8*>(a);
;         bf16x8 b1 = *reinterpret_cast<const bf16x8*>(a + 32 * KPITCH);
;         p0 = __builtin_amdgcn_mfma_f32_32x32x16_bf16(b0, qr[d0], p0, 0, 0, 0);
;         p1 = __builtin_amdgcn_mfma_f32_32x32x16_bf16(b1, qr[d0], p1, 0, 0, 0); }
; #pragma unroll
;     for (int d0 = 0; d0 < 4; ++d0) { const char* a = rb + d0 * 32;
;         bf16x8 b0 = *reinterpret_cast<const bf16x8*>(a);
;         bf16x8 b1 = *reinterpret_cast<const bf16x8*>(a + 32 * RPITCH);
;         p0 = __builtin_amdgcn_mfma_f32_32x32x16_bf16(b0, qr[8 + d0], p0, 0, 0, 0);
;         p1 = __builtin_amdgcn_mfma_f32_32x32x16_bf16(b1, qr[8 + d0], p1, 0, 0, 0); }
; }
	v_mfma_f32_32x32x16_bf16 v[66:81], v[234:237], v[122:125], v[66:81]
	v_add_f32_e32 v215, v193, v215
	v_exp_f32_e32 v219, v219
	v_add_f32_e32 v215, v223, v215
	v_mfma_f32_32x32x16_bf16 v[82:97], v[230:233], v[122:125], v[82:97]
	ds_read_b128 v[230:233], v200 offset:32992
	ds_read_b128 v[234:237], v200 offset:41696
	v_exp_f32_e32 v220, v220
	v_add_f32_e32 v215, v224, v215
	v_exp_f32_e32 v221, v221
	v_add_f32_e32 v215, v217, v215
	s_waitcnt lgkmcnt(2)
	v_mfma_f32_32x32x16_bf16 v[66:81], v[246:249], v[118:121], v[66:81]
	v_exp_f32_e32 v222, v222
	v_add_f32_e32 v215, v218, v215
	v_add_f32_e32 v215, v219, v215
	v_exp_f32_e32 v226, v228
	v_mfma_f32_32x32x16_bf16 v[82:97], v[242:245], v[118:121], v[82:97]
	ds_read_b128 v[242:245], v204
	ds_read_b128 v[246:249], v204 offset:4608
	v_add_f32_e32 v215, v220, v215
	v_exp_f32_e32 v227, v229
	v_add_f32_e32 v215, v221, v215
	v_exp_f32_e32 v181, v181
	s_waitcnt lgkmcnt(2)
	v_mfma_f32_32x32x16_bf16 v[66:81], v[234:237], v[110:113], v[66:81]
	v_add_f32_e32 v215, v222, v215
	v_add_f32_e32 v215, v225, v215
	v_add_f32_e32 v215, v226, v215
	v_add_f32_e32 v215, v227, v215
	v_mfma_f32_32x32x16_bf16 v[82:97], v[230:233], v[110:113], v[82:97]
	ds_read_b128 v[230:233], v204 offset:32
	ds_read_b128 v[234:237], v204 offset:4640
	v_add_f32_e32 v215, v181, v215
	v_mov_b32_e32 v216, v215
	v_cvt_pk_bf16_f32 v166, v166, v180
	v_cvt_pk_bf16_f32 v167, v167, v179
	s_waitcnt lgkmcnt(2)
	v_mfma_f32_32x32x16_bf16 v[66:81], v[246:249], v[114:117], v[66:81]
	v_cvt_pk_bf16_f32 v168, v168, v178
	v_cvt_pk_bf16_f32 v169, v169, v177
	v_cvt_pk_bf16_f32 v170, v170, v176
	v_cvt_pk_bf16_f32 v171, v171, v175
	v_mfma_f32_32x32x16_bf16 v[82:97], v[242:245], v[114:117], v[82:97]
	ds_read_b128 v[242:245], v204 offset:64
	ds_read_b128 v[246:249], v204 offset:4672
	v_cvt_pk_bf16_f32 v172, v172, v174
	v_cvt_pk_bf16_f32 v173, v0, v173
	v_cvt_pk_bf16_f32 v174, v190, v191
	v_cvt_pk_bf16_f32 v175, v192, v193
	s_waitcnt lgkmcnt(2)
	v_mfma_f32_32x32x16_bf16 v[82:97], v[230:233], v[106:109], v[82:97]
	v_cvt_pk_bf16_f32 v176, v223, v224
	v_cvt_pk_bf16_f32 v177, v217, v218
	v_cvt_pk_bf16_f32 v178, v219, v220
	v_cvt_pk_bf16_f32 v179, v221, v222
	v_mfma_f32_32x32x16_bf16 v[66:81], v[234:237], v[106:109], v[66:81]
	ds_read_b128 v[230:233], v204 offset:96
	ds_read_b128 v[234:237], v204 offset:4704
	v_cvt_pk_bf16_f32 v180, v225, v226
	v_cvt_pk_bf16_f32 v181, v227, v181
	v_permlane32_swap_b32_e32 v215, v216
	v_permlane32_swap_b32_e32 v166, v168
	s_waitcnt lgkmcnt(2)
	v_mfma_f32_32x32x16_bf16 v[82:97], v[242:245], v[102:105], v[82:97]
	v_permlane32_swap_b32_e32 v167, v169
	v_permlane32_swap_b32_e32 v170, v172
	v_permlane32_swap_b32_e32 v171, v173
	v_permlane32_swap_b32_e32 v174, v176
	v_mfma_f32_32x32x16_bf16 v[66:81], v[246:249], v[102:105], v[66:81]
	v_permlane32_swap_b32_e32 v175, v177
	v_permlane32_swap_b32_e32 v178, v180
	v_permlane32_swap_b32_e32 v179, v181
	s_waitcnt lgkmcnt(0)
	v_mfma_f32_32x32x16_bf16 v[82:97], v[230:233], v[98:101], v[82:97]
	v_mfma_f32_32x32x16_bf16 v[66:81], v[234:237], v[98:101], v[66:81]
	ds_read_b64_tr_b16 v[218:219], v194 offset:0x4000
	ds_read_b64_tr_b16 v[220:221], v194 offset:0x4800
	ds_read_b64_tr_b16 v[222:223], v194 offset:0x5000
	ds_read_b64_tr_b16 v[224:225], v194 offset:0x5800
	ds_read_b64_tr_b16 v[226:227], v194 offset:0x6000
	ds_read_b64_tr_b16 v[228:229], v194 offset:0x6800
	ds_read_b64_tr_b16 v[230:231], v194 offset:0x7000
	ds_read_b64_tr_b16 v[232:233], v194 offset:0x7800
	s_add_i32 s6, s82, 1
	s_cmp_lt_u32 s6, s83
	s_cselect_b64 s[90:91], -1, 0
	s_cmp_ge_u32 s6, s83
	s_cbranch_scc1 .LBB0_416
	v_mov_b32_e32 v0, v201
	v_mov_b32_e32 v162, v199
	v_mov_b32_e32 v163, v1
	v_lshl_add_u64 v[154:155], s[74:75], 0, v[0:1]
	v_add_co_u32_e32 v146, vcc, 0x1d98c000, v154
	v_lshl_add_u64 v[162:163], s[80:81], 0, v[162:163]
	s_nop 0
	v_addc_co_u32_e32 v147, vcc, 0, v155, vcc
	v_add_co_u32_e32 v150, vcc, 0x1d98e000, v154
	s_nop 1
	v_addc_co_u32_e32 v151, vcc, 0, v155, vcc
	v_add_co_u32_e32 v156, vcc, 0x1b98c000, v154
	global_load_dwordx4 v[146:149], v[146:147], off
	s_nop 0
	global_load_dwordx4 v[150:153], v[150:151], off
	v_addc_co_u32_e32 v157, vcc, 0, v155, vcc
	v_add_co_u32_e32 v158, vcc, 0x1b98e000, v154
	s_nop 1
	v_addc_co_u32_e32 v159, vcc, 0, v155, vcc
	v_add_co_u32_e32 v162, vcc, 0x18886000, v162
	global_load_dwordx4 v[154:157], v[156:157], off
	s_nop 0
	global_load_dwordx4 v[158:161], v[158:159], off
	v_addc_co_u32_e32 v163, vcc, 0, v163, vcc
	global_load_dwordx4 v[162:165], v[162:163], off

; #define SBAR() __builtin_amdgcn_sched_barrier(0)
; #define RESC(a) do { if (__any((a) < 1.f)) { if (hi == 0) al_l[r32] = (a); asm volatile("s_waitcnt lgkmcnt(0)" ::: "memory"); \
;                      for (int d_ = 0; d_ < 4; ++d_) for (int r = 0; r < 16; ++r) o[d_][r] *= al_l[crow(r, hi)]; } } while (0)
; #define MASKT(P0_, P1_, t) do { const int kb_ = KBASE(t); if (kb_ + KVBLK - 1 > qlo) mask_tile(P0_, P1_, qm - kb_); } while (0)
; __device__ __forceinline__ void partialSM(f32x16& p0, f32x16& p1, float& m_reg, float& mn, float& alpha) {
;     ...
;     constexpr float C2 = 1.4426950408889634f * ASCALE;
;     if (__builtin_expect(__all((pmax - m_reg) * ASCALE <= ATHR), 1)) { mn = m_reg; alpha = 1.f; }
;     else { mn = fmaxf(m_reg, pmax); alpha = __builtin_amdgcn_exp2f((m_reg - mn) * C2); m_reg = mn; }
;     const float mnL = -mn * C2;
; #pragma unroll
;     for (int r = 0; r < 16; ++r) p0[r] = fmaf(p0[r], C2, mnL);
; #pragma unroll
;     for (int r = 0; r < 16; ++r) p1[r] = fmaf(p1[r], C2, mnL);
; #pragma unroll
;     for (int r = 0; r < 16; ++r) p0[r] = __builtin_amdgcn_exp2f(p0[r]);
; }
; __device__ __forceinline__ void attn_block(const ABlk& cur, char* lds, ASeam& Sm, const int tid, const int wv) {
;     ...
;     for (int t = 1; t + 1 < NT; t += 2) {
;         HALF_STEP(pB0, pB1, mnB, alB, pA0, pA1, alA, t, 1, 0, 0);
;         HALF_STEP(pA0, pA1, mnA, alA, pB0, pB1, alB, t + 1, 0, 1, 1);
;     }
;     SBAR(); qkt<1>(pB0, pB1, lds, r32, hi, Sm.qr); SBAR();
;     finishSM(pA0, pA1, alA, l_reg, pa0, pa1, pa2, pa3); SBAR();
;     pv_tile<0>(o, vb0, pa0, pa1, pa2, pa3);
;     MASKT(pB0, pB1, NT - 1); partialSM(pB0, pB1, m_reg, mnB, alB); __syncthreads(); RESC(alB);
.LBB0_424:
	s_waitcnt vmcnt(0)
	v_cndmask_b32_e64 v210, v146, v210, s[6:7]
	v_mul_f32_e32 v148, 0xbdd53b94, v210
	v_mov_b32_e32 v149, v148
	s_addk_i32 s70, 0x80
	v_fmamk_f32 v166, v82, 0x3dd53b94, v148
	v_fmamk_f32 v175, v83, 0x3dd53b94, v148
	v_fmamk_f32 v167, v84, 0x3dd53b94, v148
	v_fmamk_f32 v176, v85, 0x3dd53b94, v148
	v_fmamk_f32 v168, v86, 0x3dd53b94, v148
	v_fmamk_f32 v177, v87, 0x3dd53b94, v148
	v_fmamk_f32 v169, v88, 0x3dd53b94, v148
	v_fmamk_f32 v174, v89, 0x3dd53b94, v148
	v_fmamk_f32 v165, v90, 0x3dd53b94, v148
	v_fmamk_f32 v170, v91, 0x3dd53b94, v148
	v_fmamk_f32 v171, v92, 0x3dd53b94, v148
	v_fmamk_f32 v172, v93, 0x3dd53b94, v148
	v_fmamk_f32 v162, v94, 0x3dd53b94, v148
	v_fmamk_f32 v164, v95, 0x3dd53b94, v148
	v_fmamk_f32 v163, v96, 0x3dd53b94, v148
	v_fmamk_f32 v173, v97, 0x3dd53b94, v148
	s_add_u32 s76, s76, 0x8000
	s_addc_u32 s77, s77, 0
	v_pk_fma_f32 v[160:161], v[66:67], s[84:85], v[148:149] op_sel_hi:[1,0,0]
	v_add_f32_e32 v66, v211, v212
	s_add_u32 s88, s88, 0x4000
	v_fmac_f32_e32 v66, v208, v196
	v_add_f32_e32 v196, v215, v216
	s_addc_u32 s89, s89, 0
	s_add_i32 s82, s82, 2
	v_pk_fma_f32 v[158:159], v[68:69], s[84:85], v[148:149] op_sel_hi:[1,0,0]
	v_pk_fma_f32 v[154:155], v[70:71], s[84:85], v[148:149] op_sel_hi:[1,0,0]
	v_pk_fma_f32 v[150:151], v[72:73], s[84:85], v[148:149] op_sel_hi:[1,0,0]
	v_pk_fma_f32 v[146:147], v[74:75], s[84:85], v[148:149] op_sel_hi:[1,0,0]
	v_pk_fma_f32 v[156:157], v[76:77], s[84:85], v[148:149] op_sel_hi:[1,0,0]
	v_pk_fma_f32 v[152:153], v[78:79], s[84:85], v[148:149] op_sel_hi:[1,0,0]
	v_pk_fma_f32 v[148:149], v[80:81], s[84:85], v[148:149] op_sel_hi:[1,0,0]
	v_fmac_f32_e32 v196, v66, v213
	s_cmp_ge_u32 s82, s83
	v_add_u32_e32 v209, 0xffffff80, v209
	s_waitcnt lgkmcnt(0)
	s_barrier
	s_cbranch_scc1 .LBB0_426
	v_mov_b32_e32 v208, v0
	s_branch .LBB0_408
.LBB0_426:
	v_exp_f32_e32 v166, v166
	v_exp_f32_e32 v175, v175
	v_exp_f32_e32 v167, v167
	v_exp_f32_e32 v176, v176
	v_exp_f32_e32 v168, v168
	v_exp_f32_e32 v177, v177
	v_exp_f32_e32 v169, v169
	v_exp_f32_e32 v174, v174
	v_exp_f32_e32 v165, v165
	v_exp_f32_e32 v170, v170
	v_exp_f32_e32 v171, v171
	v_exp_f32_e32 v172, v172
	v_exp_f32_e32 v162, v162
	v_exp_f32_e32 v164, v164
	v_exp_f32_e32 v163, v163
	v_exp_f32_e32 v173, v173
	ds_read_b128 v[66:69], v200 offset:50176
	s_waitcnt lgkmcnt(0)
	v_mfma_f32_32x32x16_bf16 v[82:97], v[66:69], v[142:145], 0
	ds_read_b128 v[66:69], v200 offset:58880
	s_waitcnt lgkmcnt(0)
	v_mfma_f32_32x32x16_bf16 v[66:81], v[66:69], v[142:145], 0
	ds_read_b128 v[142:145], v200 offset:50208
	s_waitcnt lgkmcnt(0)
	v_mfma_f32_32x32x16_bf16 v[82:97], v[142:145], v[138:141], v[82:97]
	ds_read_b128 v[142:145], v200 offset:58912
	s_waitcnt lgkmcnt(0)
	v_mfma_f32_32x32x16_bf16 v[66:81], v[142:145], v[138:141], v[66:81]
	ds_read_b128 v[138:141], v200 offset:50240
	s_waitcnt lgkmcnt(0)
	v_mfma_f32_32x32x16_bf16 v[82:97], v[138:141], v[134:137], v[82:97]
	ds_read_b128 v[138:141], v200 offset:58944
	s_waitcnt lgkmcnt(0)
	v_mfma_f32_32x32x16_bf16 v[66:81], v[138:141], v[134:137], v[66:81]
	ds_read_b128 v[134:137], v200 offset:50272
	s_waitcnt lgkmcnt(0)
	v_mfma_f32_32x32x16_bf16 v[82:97], v[134:137], v[130:133], v[82:97]
	ds_read_b128 v[134:137], v200 offset:58976
	s_waitcnt lgkmcnt(0)
	v_mfma_f32_32x32x16_bf16 v[66:81], v[134:137], v[130:133], v[66:81]
	ds_read_b128 v[130:133], v200 offset:50304
	s_waitcnt lgkmcnt(0)
	v_mfma_f32_32x32x16_bf16 v[82:97], v[130:133], v[126:129], v[82:97]
	ds_read_b128 v[130:133], v200 offset:59008
	s_waitcnt lgkmcnt(0)
	v_mfma_f32_32x32x16_bf16 v[66:81], v[130:133], v[126:129], v[66:81]
	ds_read_b128 v[126:129], v200 offset:50336
	s_waitcnt lgkmcnt(0)
	v_mfma_f32_32x32x16_bf16 v[82:97], v[126:129], v[122:125], v[82:97]
	ds_read_b128 v[126:129], v200 offset:59040
	s_waitcnt lgkmcnt(0)
	v_mfma_f32_32x32x16_bf16 v[66:81], v[126:129], v[122:125], v[66:81]
	ds_read_b128 v[122:125], v200 offset:50368
	s_waitcnt lgkmcnt(0)
	v_mfma_f32_32x32x16_bf16 v[82:97], v[122:125], v[118:121], v[82:97]
	ds_read_b128 v[122:125], v200 offset:59072
	s_waitcnt lgkmcnt(0)
	v_mfma_f32_32x32x16_bf16 v[66:81], v[122:125], v[118:121], v[66:81]
	ds_read_b128 v[118:121], v200 offset:50400
	s_waitcnt lgkmcnt(0)
	v_mfma_f32_32x32x16_bf16 v[82:97], v[118:121], v[110:113], v[82:97]
	ds_read_b128 v[118:121], v200 offset:59104
	s_waitcnt lgkmcnt(0)
	v_mfma_f32_32x32x16_bf16 v[66:81], v[118:121], v[110:113], v[66:81]
	ds_read_b128 v[110:113], v205
	s_waitcnt lgkmcnt(0)
	v_mfma_f32_32x32x16_bf16 v[82:97], v[110:113], v[114:117], v[82:97]
	ds_read_b128 v[110:113], v205 offset:4608
	s_waitcnt lgkmcnt(0)
	v_mfma_f32_32x32x16_bf16 v[66:81], v[110:113], v[114:117], v[66:81]
	ds_read_b128 v[110:113], v205 offset:32
	s_waitcnt lgkmcnt(0)
	v_mfma_f32_32x32x16_bf16 v[82:97], v[110:113], v[106:109], v[82:97]
	ds_read_b128 v[110:113], v205 offset:4640
	s_waitcnt lgkmcnt(0)
	v_mfma_f32_32x32x16_bf16 v[66:81], v[110:113], v[106:109], v[66:81]
	ds_read_b128 v[106:109], v205 offset:64
	s_waitcnt lgkmcnt(0)
	v_mfma_f32_32x32x16_bf16 v[82:97], v[106:109], v[102:105], v[82:97]
	ds_read_b128 v[106:109], v205 offset:4672
	s_waitcnt lgkmcnt(0)
	v_mfma_f32_32x32x16_bf16 v[66:81], v[106:109], v[102:105], v[66:81]
	ds_read_b128 v[102:105], v205 offset:96
	s_waitcnt lgkmcnt(0)
	v_mfma_f32_32x32x16_bf16 v[82:97], v[102:105], v[98:101], v[82:97]
	ds_read_b128 v[102:105], v205 offset:4704
	s_waitcnt lgkmcnt(0)
; __device__ __forceinline__ void finishSM(f32x16& p0, f32x16& p1, float alpha, float& l_reg, bf16x8& pa0, bf16x8& pa1, bf16x8& pa2, bf16x8& pa3) {
; #pragma unroll
;     for (int r = 0; r < 16; ++r) p1[r] = __builtin_amdgcn_exp2f(p1[r]);
;     float ps = 0;
; #pragma unroll
;     for (int r = 0; r < 16; ++r) ps += p0[r];
; #pragma unroll
;     for (int r = 0; r < 16; ++r) ps += p1[r];
;     { auto rr = __builtin_amdgcn_permlane32_swap(__float_as_uint(ps), __float_as_uint(ps), false, false);
;       ps = __uint_as_float(rr[0]) + __uint_as_float(rr[1]); }
;     l_reg = l_reg * alpha + ps;
;     ...
;     PK4(p0, 0, pa0); PK4(p0, 8, pa1); PK4(p1, 0, pa2); PK4(p1, 8, pa3);
;     ...
; }
; template <int VB>
; __device__ __forceinline__ void pv_tile(f32x16* o, int vb0, bf16x8 pa0, bf16x8 pa1, bf16x8 pa2, bf16x8 pa3) {
;     ...
;     PV_D0(0); PV_D0(1); PV_D0(2); PV_D0(3);
	v_mfma_f32_32x32x16_bf16 v[66:81], v[102:105], v[98:101], v[66:81]
	v_add_f32_e32 v98, 0, v166
	v_add_f32_e32 v98, v175, v98
	v_add_f32_e32 v98, v167, v98
	v_add_f32_e32 v98, v176, v98
	v_add_f32_e32 v98, v168, v98
	v_add_f32_e32 v98, v177, v98
	v_add_f32_e32 v98, v169, v98
	v_add_f32_e32 v98, v174, v98
	v_add_f32_e32 v98, v165, v98
	v_add_f32_e32 v98, v170, v98
	v_add_f32_e32 v98, v171, v98
	v_add_f32_e32 v98, v172, v98
	v_exp_f32_e32 v108, v160
	v_add_f32_e32 v98, v162, v98
	v_exp_f32_e32 v109, v161
	v_add_f32_e32 v98, v164, v98
	v_exp_f32_e32 v110, v158
	v_add_f32_e32 v98, v163, v98
	v_exp_f32_e32 v111, v159
	v_add_f32_e32 v98, v173, v98
	v_exp_f32_e32 v112, v154
	v_add_f32_e32 v98, v108, v98
	v_exp_f32_e32 v113, v155
	v_add_f32_e32 v98, v109, v98
	v_exp_f32_e32 v114, v150
	v_add_f32_e32 v98, v110, v98
	v_exp_f32_e32 v115, v151
	v_add_f32_e32 v98, v111, v98
	v_exp_f32_e32 v116, v146
	v_add_f32_e32 v98, v112, v98
	v_exp_f32_e32 v117, v147
	v_add_f32_e32 v98, v113, v98
	v_exp_f32_e32 v118, v156
	v_add_f32_e32 v98, v114, v98
	v_exp_f32_e32 v119, v157
	v_add_f32_e32 v98, v115, v98
	v_exp_f32_e32 v120, v152
	v_add_f32_e32 v98, v116, v98
	v_exp_f32_e32 v121, v153
	v_add_f32_e32 v98, v117, v98
	v_exp_f32_e32 v122, v148
	v_add_f32_e32 v98, v118, v98
	v_exp_f32_e32 v123, v149
	v_add_f32_e32 v98, v119, v98
	v_add_f32_e32 v98, v120, v98
	v_add_f32_e32 v98, v121, v98
	v_add_f32_e32 v98, v122, v98
	v_add_f32_e32 v98, v123, v98
	v_mov_b32_e32 v99, v98
	s_nop 1
	v_permlane32_swap_b32_e32 v98, v99
	v_cvt_pk_bf16_f32 v100, v166, v175
	v_cvt_pk_bf16_f32 v101, v167, v176
	v_cvt_pk_bf16_f32 v102, v168, v177
	v_cvt_pk_bf16_f32 v103, v169, v174
	v_cvt_pk_bf16_f32 v104, v165, v170
	v_cvt_pk_bf16_f32 v105, v171, v172
	v_cvt_pk_bf16_f32 v106, v162, v164
	v_cvt_pk_bf16_f32 v107, v163, v173
	v_cvt_pk_bf16_f32 v108, v108, v109
	v_cvt_pk_bf16_f32 v109, v110, v111
	v_cvt_pk_bf16_f32 v110, v112, v113
	v_cvt_pk_bf16_f32 v111, v114, v115
	v_cvt_pk_bf16_f32 v112, v116, v117
	v_cvt_pk_bf16_f32 v113, v118, v119
	v_cvt_pk_bf16_f32 v114, v120, v121
	v_cvt_pk_bf16_f32 v115, v122, v123
	s_nop 0
	v_permlane32_swap_b32_e32 v100, v102
	v_permlane32_swap_b32_e32 v101, v103
	v_permlane32_swap_b32_e32 v104, v106
	v_permlane32_swap_b32_e32 v105, v107
	v_permlane32_swap_b32_e32 v108, v110
	v_permlane32_swap_b32_e32 v109, v111
	v_permlane32_swap_b32_e32 v112, v114
	v_permlane32_swap_b32_e32 v113, v115
	ds_read_b64_tr_b16 v[116:117], v194 offset:0
	ds_read_b64_tr_b16 v[118:119], v194 offset:0x800
	ds_read_b64_tr_b16 v[120:121], v194 offset:0x1000
	ds_read_b64_tr_b16 v[122:123], v194 offset:0x1800
	ds_read_b64_tr_b16 v[124:125], v194 offset:0x2000
	ds_read_b64_tr_b16 v[126:127], v194 offset:0x2800
	ds_read_b64_tr_b16 v[128:129], v194 offset:0x3000
	ds_read_b64_tr_b16 v[130:131], v194 offset:0x3800
	s_waitcnt lgkmcnt(0)
	s_nop 0
	v_mfma_f32_32x32x16_bf16 v[50:65], v[100:103], v[116:119], v[50:65]
	ds_read_b64_tr_b16 v[116:117], v194 offset:0x200
	ds_read_b64_tr_b16 v[118:119], v194 offset:0xa00
	v_mfma_f32_32x32x16_bf16 v[50:65], v[104:107], v[120:123], v[50:65]
	ds_read_b64_tr_b16 v[120:121], v194 offset:0x1200
	ds_read_b64_tr_b16 v[122:123], v194 offset:0x1a00
	v_mfma_f32_32x32x16_bf16 v[50:65], v[108:111], v[124:127], v[50:65]
	ds_read_b64_tr_b16 v[124:125], v194 offset:0x2200
	ds_read_b64_tr_b16 v[126:127], v194 offset:0x2a00
	v_mfma_f32_32x32x16_bf16 v[50:65], v[112:115], v[128:131], v[50:65]
	ds_read_b64_tr_b16 v[128:129], v194 offset:0x3200
	ds_read_b64_tr_b16 v[130:131], v194 offset:0x3a00
	s_waitcnt lgkmcnt(0)
	v_mfma_f32_32x32x16_bf16 v[34:49], v[100:103], v[116:119], v[34:49]
	ds_read_b64_tr_b16 v[116:117], v194 offset:0x400
	ds_read_b64_tr_b16 v[118:119], v194 offset:0xc00
	v_mfma_f32_32x32x16_bf16 v[34:49], v[104:107], v[120:123], v[34:49]
	ds_read_b64_tr_b16 v[120:121], v194 offset:0x1400
	ds_read_b64_tr_b16 v[122:123], v194 offset:0x1c00
	v_mfma_f32_32x32x16_bf16 v[34:49], v[108:111], v[124:127], v[34:49]
	ds_read_b64_tr_b16 v[124:125], v194 offset:0x2400
	ds_read_b64_tr_b16 v[126:127], v194 offset:0x2c00
	v_mfma_f32_32x32x16_bf16 v[34:49], v[112:115], v[128:131], v[34:49]
	ds_read_b64_tr_b16 v[128:129], v194 offset:0x3400
	ds_read_b64_tr_b16 v[130:131], v194 offset:0x3c00
	s_waitcnt lgkmcnt(0)
	v_mfma_f32_32x32x16_bf16 v[18:33], v[100:103], v[116:119], v[18:33]
	ds_read_b64_tr_b16 v[116:117], v194 offset:0x600
	ds_read_b64_tr_b16 v[118:119], v194 offset:0xe00
	v_mfma_f32_32x32x16_bf16 v[18:33], v[104:107], v[120:123], v[18:33]
	ds_read_b64_tr_b16 v[120:121], v194 offset:0x1600
	ds_read_b64_tr_b16 v[122:123], v194 offset:0x1e00
	v_mfma_f32_32x32x16_bf16 v[18:33], v[108:111], v[124:127], v[18:33]
	ds_read_b64_tr_b16 v[124:125], v194 offset:0x2600
	ds_read_b64_tr_b16 v[126:127], v194 offset:0x2e00
	v_mfma_f32_32x32x16_bf16 v[18:33], v[112:115], v[128:131], v[18:33]
	ds_read_b64_tr_b16 v[128:129], v194 offset:0x3600
	ds_read_b64_tr_b16 v[130:131], v194 offset:0x3e00
	s_waitcnt lgkmcnt(0)
	v_mfma_f32_32x32x16_bf16 v[2:17], v[100:103], v[116:119], v[2:17]
	s_cmpk_lt_i32 s95, 0xff
	v_mfma_f32_32x32x16_bf16 v[2:17], v[104:107], v[120:123], v[2:17]
	v_mfma_f32_32x32x16_bf16 v[2:17], v[108:111], v[124:127], v[2:17]
	v_mfma_f32_32x32x16_bf16 v[2:17], v[112:115], v[128:131], v[2:17]
	s_cbranch_scc0 .LBB0_428
; #define RESC(a) do { if (__any((a) < 1.f)) { if (hi == 0) al_l[r32] = (a); asm volatile("s_waitcnt lgkmcnt(0)" ::: "memory"); \
;                      for (int d_ = 0; d_ < 4; ++d_) for (int r = 0; r < 16; ++r) o[d_][r] *= al_l[crow(r, hi)]; } } while (0)
; #define MASKT(P0_, P1_, t) do { const int kb_ = KBASE(t); if (kb_ + KVBLK - 1 > qlo) mask_tile(P0_, P1_, qm - kb_); } while (0)
; __device__ __forceinline__ void mask_tile(f32x16& p0, f32x16& p1, int dq) {
;     const float NEG = -__builtin_inff();
; #pragma unroll
;     for (int r = 0; r < 16; ++r) { const int c = (r & 3) + 8 * (r >> 2);
;         if (dq - c < 0) p0[r] = NEG;
;         if (dq - c - 32 < 0) p1[r] = NEG; }
; }
; __device__ __forceinline__ void attn_block(const ABlk& cur, char* lds, ASeam& Sm, const int tid, const int wv) {
;     ...
;     MASKT(pB0, pB1, NT - 1); partialSM(pB0, pB1, m_reg, mnB, alB); __syncthreads(); RESC(alB);
	v_subrev_u32_e32 v100, s94, v197
	v_add_u32_e32 v100, 0xffffff40, v100
	v_cmp_gt_i32_e64 s[64:65], 26, v100
	v_cmp_gt_i32_e64 s[66:67], 27, v100
	v_cmp_gt_i32_e64 s[62:63], 25, v100
	s_and_b64 s[64:65], s[66:67], s[64:65]
	v_cmp_gt_i32_e64 s[60:61], 24, v100
	s_and_b64 s[62:63], s[64:65], s[62:63]
	v_cmp_gt_i32_e64 s[58:59], 19, v100
	s_and_b64 s[60:61], s[62:63], s[60:61]
	v_cmp_gt_i32_e64 s[56:57], 18, v100
	s_and_b64 s[58:59], s[60:61], s[58:59]
	v_cmp_gt_i32_e64 s[54:55], 17, v100
	s_and_b64 s[56:57], s[58:59], s[56:57]
	v_cmp_gt_i32_e64 s[52:53], 16, v100
	s_and_b64 s[54:55], s[56:57], s[54:55]
	v_cmp_gt_i32_e64 s[50:51], 11, v100
	s_and_b64 s[52:53], s[54:55], s[52:53]
	v_cmp_gt_i32_e64 s[48:49], 10, v100
	s_and_b64 s[50:51], s[52:53], s[50:51]
	v_cmp_gt_i32_e64 s[46:47], 9, v100
	s_and_b64 s[48:49], s[50:51], s[48:49]
	v_cmp_gt_i32_e64 s[44:45], 8, v100
	s_and_b64 s[46:47], s[48:49], s[46:47]
	v_cmp_gt_i32_e64 s[42:43], 3, v100
	s_and_b64 s[44:45], s[46:47], s[44:45]
	v_cmp_gt_i32_e64 s[40:41], 2, v100
	s_and_b64 s[42:43], s[44:45], s[42:43]
	v_cmp_gt_i32_e64 s[38:39], 1, v100
	s_and_b64 s[40:41], s[42:43], s[40:41]
	v_cmp_gt_i32_e64 s[36:37], 0, v100
	s_and_b64 s[38:39], s[40:41], s[38:39]
	s_and_b64 s[36:37], s[38:39], s[36:37]
	v_cmp_gt_i32_e64 s[34:35], 58, v100
	v_cndmask_b32_e64 v82, v82, v186, s[36:37]
	v_cmp_gt_i32_e64 s[36:37], 59, v100
	v_cmp_gt_i32_e64 s[30:31], 57, v100
	s_and_b64 s[34:35], s[36:37], s[34:35]
	v_cmp_gt_i32_e64 s[28:29], 56, v100
	s_and_b64 s[30:31], s[34:35], s[30:31]
	v_cmp_gt_i32_e64 s[26:27], 51, v100
	s_and_b64 s[28:29], s[30:31], s[28:29]
	v_cmp_gt_i32_e64 s[24:25], 50, v100
	s_and_b64 s[26:27], s[28:29], s[26:27]
	v_cmp_gt_i32_e64 s[22:23], 49, v100
	s_and_b64 s[24:25], s[26:27], s[24:25]
	v_cmp_gt_i32_e64 s[20:21], 48, v100
	s_and_b64 s[22:23], s[24:25], s[22:23]
	v_cmp_gt_i32_e64 s[18:19], 43, v100
	s_and_b64 s[20:21], s[22:23], s[20:21]
	v_cmp_gt_i32_e64 s[16:17], 42, v100
	s_and_b64 s[18:19], s[20:21], s[18:19]
	v_cmp_gt_i32_e64 s[14:15], 41, v100
	s_and_b64 s[16:17], s[18:19], s[16:17]
	v_cmp_gt_i32_e64 s[12:13], 40, v100
	s_and_b64 s[14:15], s[16:17], s[14:15]
	v_cmp_gt_i32_e64 s[10:11], 35, v100
	s_and_b64 s[12:13], s[14:15], s[12:13]
	v_cmp_gt_i32_e64 s[8:9], 34, v100
	s_and_b64 s[10:11], s[12:13], s[10:11]
	v_cmp_gt_i32_e64 s[6:7], 33, v100
	s_and_b64 s[8:9], s[10:11], s[8:9]
	v_cmp_gt_i32_e32 vcc, 32, v100
	s_and_b64 s[6:7], s[8:9], s[6:7]
	s_and_b64 vcc, s[6:7], vcc
	v_cndmask_b32_e64 v97, v97, v186, s[66:67]
	v_cndmask_b32_e64 v96, v96, v186, s[64:65]
	v_cndmask_b32_e64 v95, v95, v186, s[62:63]
	v_cndmask_b32_e64 v94, v94, v186, s[60:61]
	v_cndmask_b32_e64 v93, v93, v186, s[58:59]
	v_cndmask_b32_e64 v92, v92, v186, s[56:57]
	v_cndmask_b32_e64 v91, v91, v186, s[54:55]
	v_cndmask_b32_e64 v90, v90, v186, s[52:53]
	v_cndmask_b32_e64 v89, v89, v186, s[50:51]
	v_cndmask_b32_e64 v88, v88, v186, s[48:49]
	v_cndmask_b32_e64 v87, v87, v186, s[46:47]
	v_cndmask_b32_e64 v86, v86, v186, s[44:45]
	v_cndmask_b32_e64 v85, v85, v186, s[42:43]
	v_cndmask_b32_e64 v84, v84, v186, s[40:41]
	v_cndmask_b32_e64 v83, v83, v186, s[38:39]
	v_cndmask_b32_e64 v81, v81, v186, s[36:37]
	v_cndmask_b32_e64 v80, v80, v186, s[34:35]
	v_cndmask_b32_e64 v79, v79, v186, s[30:31]
	v_cndmask_b32_e64 v78, v78, v186, s[28:29]
	v_cndmask_b32_e64 v77, v77, v186, s[26:27]
	v_cndmask_b32_e64 v76, v76, v186, s[24:25]
	v_cndmask_b32_e64 v75, v75, v186, s[22:23]
	v_cndmask_b32_e64 v74, v74, v186, s[20:21]
	v_cndmask_b32_e64 v73, v73, v186, s[18:19]
	v_cndmask_b32_e64 v72, v72, v186, s[16:17]
	v_cndmask_b32_e64 v71, v71, v186, s[14:15]
	v_cndmask_b32_e64 v70, v70, v186, s[12:13]
	v_cndmask_b32_e64 v69, v69, v186, s[10:11]
	v_cndmask_b32_e64 v68, v68, v186, s[8:9]
	v_cndmask_b32_e64 v67, v67, v186, s[6:7]
	v_cndmask_b32_e32 v66, v66, v186, vcc
